# S31: S30 + ln1_router wave sums / router reduce-scatter / softmax reductions: 54 ds_bpermute -> exact-xor DPP (quad_perm, half_mirror+quad reverse, row_ror:8) and permlane16/32 swaps
# speedup vs baseline: 1.0018x; 1.0008x over previous
; __device__ __forceinline__ void ln_norm_only(f32x4 (&v)[8]) {
;     float s = 0.f;
; #pragma unroll
;     for (int j = 0; j < 8; ++j) s += (v[j][0] + v[j][1]) + (v[j][2] + v[j][3]);
;     const float mean = wave_sum(s) * (1.0f / DM); float q = 0.f;
; #pragma unroll
;     for (int j = 0; j < 8; ++j) { v[j] = v[j] - mean; q += (v[j][0] * v[j][0] + v[j][1] * v[j][1]) + (v[j][2] * v[j][2] + v[j][3] * v[j][3]); }
;     const float rstd = 1.0f / sqrtf(wave_sum(q) * (1.0f / DM) + LN_EPS);
; __device__ __forceinline__ void ln1_router(Frame& F, int l, int nrows) {
;     ...
;         for (int q = 0; q < 2; ++q) { const int row = rows[q];
;             ln_norm_only(v[q]);
.LBB0_1316:
	v_and_b32_e32 v138, 64, v185
	v_add_u32_e32 v148, 64, v138
	v_xor_b32_e32 v138, 1, v185
	v_cmp_lt_i32_e32 vcc, v138, v148
	v_mov_b32_e32 v139, v118
	v_mov_b32_e32 v140, v111
	v_cndmask_b32_e32 v138, v185, v138, vcc
	v_lshlrev_b32_e32 v146, 2, v138
	v_mov_b32_e32 v138, v110
	v_mov_b32_e32 v141, v119
	v_pk_add_f32 v[138:139], v[138:139], v[140:141]
	v_mov_b32_e32 v140, v112
	v_mov_b32_e32 v141, v120
	v_mov_b32_e32 v142, v113
	v_mov_b32_e32 v143, v121
	v_pk_add_f32 v[140:141], v[140:141], v[142:143]
	v_mov_b32_e32 v142, v102
	v_pk_add_f32 v[138:139], v[138:139], v[140:141]
	v_mov_b32_e32 v140, v103
	v_mov_b32_e32 v141, v104
	v_mov_b32_e32 v143, v105
	v_pk_add_f32 v[140:141], v[140:141], v[142:143]
	v_add_f32_e32 v139, 0, v139
	v_pk_add_f32 v[140:141], v[140:141], v[140:141] op_sel_hi:[0,1]
	v_add_f32_e32 v139, v138, v139
	v_add_f32_e32 v143, v98, v99
	v_add_f32_e32 v145, v100, v101
	v_mov_b32_e32 v142, v114
	v_mov_b32_e32 v144, v115
	v_mov_b32_e32 v140, v116
	v_mov_b32_e32 v138, v117
	v_pk_add_f32 v[142:143], v[142:143], v[144:145]
	v_pk_add_f32 v[138:139], v[140:141], v[138:139]
	v_mov_b32_e32 v140, v107
	v_pk_add_f32 v[138:139], v[142:143], v[138:139]
	v_mov_b32_e32 v141, v108
	v_mov_b32_e32 v142, v106
	v_mov_b32_e32 v143, v109
	v_pk_add_f32 v[140:141], v[140:141], v[142:143]
	v_pk_add_f32 v[138:139], v[138:139], v[138:139] op_sel_hi:[0,1]
	v_pk_add_f32 v[140:141], v[140:141], v[140:141] op_sel_hi:[0,1]
	v_add_f32_e32 v143, v126, v127
	v_add_f32_e32 v145, v128, v129
	v_mov_b32_e32 v142, v122
	v_mov_b32_e32 v144, v123
	v_mov_b32_e32 v140, v124
	v_mov_b32_e32 v138, v125
	v_pk_add_f32 v[142:143], v[142:143], v[144:145]
	v_pk_add_f32 v[138:139], v[140:141], v[138:139]
	v_xor_b32_e32 v140, 2, v185
	v_pk_add_f32 v[138:139], v[142:143], v[138:139]
	v_cmp_lt_i32_e32 vcc, v140, v148
	v_add_f32_e32 v138, v138, v139
	s_nop 1
	v_mov_b32_dpp v139, v138 quad_perm:[1,0,3,2] row_mask:0xf bank_mask:0xf
	v_cndmask_b32_e32 v140, v185, v140, vcc
	v_lshlrev_b32_e32 v211, 2, v140
	v_xor_b32_e32 v140, 4, v185
	v_cmp_lt_i32_e32 vcc, v140, v148
	s_waitcnt lgkmcnt(0)
	v_add_f32_e32 v138, v138, v139
	s_nop 1
	v_mov_b32_dpp v139, v138 quad_perm:[2,3,0,1] row_mask:0xf bank_mask:0xf
	v_cndmask_b32_e32 v140, v185, v140, vcc
	v_lshlrev_b32_e32 v212, 2, v140
	v_xor_b32_e32 v140, 8, v185
	v_cmp_lt_i32_e32 vcc, v140, v148
	s_waitcnt lgkmcnt(0)
	v_add_f32_e32 v138, v138, v139
	s_nop 1
	v_mov_b32_dpp v139, v138 row_half_mirror row_mask:0xf bank_mask:0xf
	s_nop 1
	v_mov_b32_dpp v139, v139 quad_perm:[3,2,1,0] row_mask:0xf bank_mask:0xf
	v_cndmask_b32_e32 v140, v185, v140, vcc
	v_lshlrev_b32_e32 v213, 2, v140
	v_xor_b32_e32 v140, 16, v185
	v_cmp_lt_i32_e32 vcc, v140, v148
	s_waitcnt lgkmcnt(0)
	v_add_f32_e32 v138, v138, v139
	s_nop 1
	v_mov_b32_dpp v139, v138 row_ror:8 row_mask:0xf bank_mask:0xf
	v_cndmask_b32_e32 v140, v185, v140, vcc
	v_lshlrev_b32_e32 v214, 2, v140
	v_xor_b32_e32 v140, 32, v185
	v_cmp_lt_i32_e32 vcc, v140, v148
	s_waitcnt lgkmcnt(0)
	v_add_f32_e32 v138, v138, v139
	v_mov_b32_e32 v139, v138
	s_nop 1
	v_permlane16_swap_b32_e32 v138, v139
	v_cndmask_b32_e32 v140, v185, v140, vcc
	v_lshlrev_b32_e32 v215, 2, v140
	s_mov_b32 s11, 0xf800000
	s_cmp_lt_i32 s10, s16
	s_waitcnt lgkmcnt(0)
	v_add_f32_e32 v138, v138, v139
	v_mov_b32_e32 v139, v138
	s_nop 1
	v_permlane32_swap_b32_e32 v138, v139
	s_cselect_b64 s[14:15], -1, 0
	s_ashr_i32 s9, s8, 31
	s_waitcnt lgkmcnt(0)
	v_add_f32_e32 v148, v138, v139
	v_fmamk_f32 v119, v148, 0xba000000, v119
	v_fmamk_f32 v111, v148, 0xba000000, v111
	v_fmamk_f32 v121, v148, 0xba000000, v121
	v_fmac_f32_e32 v118, 0xba000000, v148
	v_fmamk_f32 v113, v148, 0xba000000, v113
	v_fmac_f32_e32 v110, 0xba000000, v148
	v_mov_b32_e32 v140, v119
	v_mov_b32_e32 v141, v111
	v_fmamk_f32 v120, v148, 0xba000000, v120
	v_fmamk_f32 v112, v148, 0xba000000, v112
	v_mov_b32_e32 v138, v118
	v_mov_b32_e32 v139, v110
	v_pk_mul_f32 v[140:141], v[140:141], v[140:141]
	v_mov_b32_e32 v142, v121
	v_mov_b32_e32 v143, v113
	v_pk_fma_f32 v[138:139], v[138:139], v[138:139], v[140:141]
	v_mov_b32_e32 v140, v120
	v_mov_b32_e32 v141, v112
	v_pk_mul_f32 v[142:143], v[142:143], v[142:143]
	v_fmamk_f32 v103, v148, 0xba000000, v103
	v_pk_fma_f32 v[140:141], v[140:141], v[140:141], v[142:143]
	v_fmamk_f32 v102, v148, 0xba000000, v102
	v_pk_add_f32 v[138:139], v[138:139], v[140:141]
	v_fmamk_f32 v105, v148, 0xba000000, v105
	v_fmac_f32_e32 v104, 0xba000000, v148
	v_pk_add_f32 v[138:139], v[138:139], v[138:139] op_sel_hi:[0,1]
	v_pk_mul_f32 v[140:141], v[104:105], v[104:105]
	v_pk_mul_f32 v[142:143], v[102:103], v[102:103]
	v_fmamk_f32 v98, v148, 0xba000000, v98
	v_pk_mov_b32 v[144:145], v[142:143], v[140:141] op_sel:[1,0]
	v_mov_b32_e32 v143, v141
	v_fmamk_f32 v99, v148, 0xba000000, v99
	v_fmac_f32_e32 v100, 0xba000000, v148
	v_mul_f32_e32 v138, v98, v98
	v_pk_add_f32 v[140:141], v[144:145], v[142:143]
	v_fmamk_f32 v101, v148, 0xba000000, v101
	v_pk_fma_f32 v[142:143], v[98:99], v[98:99], v[138:139] op_sel_hi:[1,1,0]
	v_mul_f32_e32 v138, v100, v100
	v_pk_add_f32 v[140:141], v[140:141], v[140:141] op_sel_hi:[0,1]
	v_pk_fma_f32 v[144:145], v[100:101], v[100:101], v[138:139] op_sel_hi:[1,1,0]
	v_fmamk_f32 v117, v148, 0xba000000, v117
	v_fmamk_f32 v116, v148, 0xba000000, v116
	v_fmamk_f32 v115, v148, 0xba000000, v115
	v_fmac_f32_e32 v114, 0xba000000, v148
	v_mul_f32_e32 v142, v114, v114
	v_mul_f32_e32 v144, v115, v115
	v_mul_f32_e32 v140, v116, v116
	v_mul_f32_e32 v138, v117, v117
	v_pk_add_f32 v[142:143], v[142:143], v[144:145]
	v_pk_add_f32 v[138:139], v[140:141], v[138:139]
	v_fmamk_f32 v107, v148, 0xba000000, v107
	v_pk_add_f32 v[138:139], v[142:143], v[138:139]
; #define LAS __attribute__((address_space(3)))
; __device__ __forceinline__ void ln_norm_only(f32x4 (&v)[8]) {
;     ...
;     const float mean = wave_sum(s) * (1.0f / DM); float q = 0.f;
; #pragma unroll
;     for (int j = 0; j < 8; ++j) { v[j] = v[j] - mean; q += (v[j][0] * v[j][0] + v[j][1] * v[j][1]) + (v[j][2] * v[j][2] + v[j][3] * v[j][3]); }
;     const float rstd = 1.0f / sqrtf(wave_sum(q) * (1.0f / DM) + LN_EPS);
; #pragma unroll
;     for (int j = 0; j < 8; ++j) v[j] = v[j] * rstd;
; }
; __device__ __forceinline__ void ln1_router(Frame& F, int l, int nrows) {
;     ...
; #pragma unroll
;             for (int j = 0; j < 8; ++j) { const int cc = 256 * j + 4 * F.lane; v[q][j] = v[q][j] * *(const LAS f32x4*)(PWS + cc) + *(const LAS f32x4*)(PBS + cc); }
	v_fmamk_f32 v106, v148, 0xba000000, v106
	v_fmamk_f32 v109, v148, 0xba000000, v109
	v_fmac_f32_e32 v108, 0xba000000, v148
	v_pk_add_f32 v[138:139], v[138:139], v[138:139] op_sel_hi:[0,1]
	v_pk_mul_f32 v[140:141], v[108:109], v[108:109]
	v_pk_mul_f32 v[142:143], v[106:107], v[106:107]
	v_fmamk_f32 v126, v148, 0xba000000, v126
	v_pk_mov_b32 v[144:145], v[142:143], v[140:141] op_sel:[1,0]
	v_mov_b32_e32 v143, v141
	v_fmamk_f32 v127, v148, 0xba000000, v127
	v_fmac_f32_e32 v128, 0xba000000, v148
	v_mul_f32_e32 v138, v126, v126
	v_pk_add_f32 v[140:141], v[144:145], v[142:143]
	v_fmamk_f32 v129, v148, 0xba000000, v129
	v_pk_fma_f32 v[142:143], v[126:127], v[126:127], v[138:139] op_sel_hi:[1,1,0]
	v_mul_f32_e32 v138, v128, v128
	v_pk_add_f32 v[140:141], v[140:141], v[140:141] op_sel_hi:[0,1]
	v_pk_fma_f32 v[144:145], v[128:129], v[128:129], v[138:139] op_sel_hi:[1,1,0]
	v_fmamk_f32 v125, v148, 0xba000000, v125
	v_fmamk_f32 v124, v148, 0xba000000, v124
	v_fmamk_f32 v123, v148, 0xba000000, v123
	v_fmac_f32_e32 v122, 0xba000000, v148
	v_mul_f32_e32 v142, v122, v122
	v_mul_f32_e32 v144, v123, v123
	v_mul_f32_e32 v140, v124, v124
	v_mul_f32_e32 v138, v125, v125
	v_pk_add_f32 v[142:143], v[142:143], v[144:145]
	v_pk_add_f32 v[138:139], v[140:141], v[138:139]
	s_nop 0
	v_pk_add_f32 v[138:139], v[142:143], v[138:139]
	s_nop 0
	v_add_f32_e32 v138, v138, v139
	s_nop 1
	v_mov_b32_dpp v139, v138 quad_perm:[1,0,3,2] row_mask:0xf bank_mask:0xf
	s_waitcnt lgkmcnt(0)
	v_add_f32_e32 v138, v138, v139
	s_nop 1
	v_mov_b32_dpp v139, v138 quad_perm:[2,3,0,1] row_mask:0xf bank_mask:0xf
	s_waitcnt lgkmcnt(0)
	v_add_f32_e32 v138, v138, v139
	s_nop 1
	v_mov_b32_dpp v139, v138 row_half_mirror row_mask:0xf bank_mask:0xf
	s_nop 1
	v_mov_b32_dpp v139, v139 quad_perm:[3,2,1,0] row_mask:0xf bank_mask:0xf
	s_waitcnt lgkmcnt(0)
	v_add_f32_e32 v138, v138, v139
	s_nop 1
	v_mov_b32_dpp v139, v138 row_ror:8 row_mask:0xf bank_mask:0xf
	s_waitcnt lgkmcnt(0)
	v_add_f32_e32 v138, v138, v139
	v_mov_b32_e32 v139, v138
	s_nop 1
	v_permlane16_swap_b32_e32 v138, v139
	s_waitcnt lgkmcnt(0)
	v_add_f32_e32 v138, v138, v139
	v_mov_b32_e32 v139, v138
	s_nop 1
	v_permlane32_swap_b32_e32 v138, v139
	s_waitcnt lgkmcnt(0)
	v_add_f32_e32 v138, v138, v139
	v_fmamk_f32 v138, v138, 0x3a000000, v179
	v_mul_f32_e32 v139, 0x4f800000, v138
	v_cmp_gt_f32_e32 vcc, s11, v138
	s_nop 1
	v_cndmask_b32_e32 v138, v138, v139, vcc
	v_sqrt_f32_e32 v139, v138
	s_nop 0
	v_add_u32_e32 v140, -1, v139
	v_fma_f32 v141, -v140, v139, v138
	v_cmp_ge_f32_e64 s[0:1], 0, v141
	v_add_u32_e32 v141, 1, v139
	s_nop 0
	v_cndmask_b32_e64 v140, v139, v140, s[0:1]
	v_fma_f32 v139, -v141, v139, v138
	v_cmp_lt_f32_e64 s[0:1], 0, v139
	s_nop 1
	v_cndmask_b32_e64 v139, v140, v141, s[0:1]
	v_mul_f32_e32 v140, 0x37800000, v139
	v_cndmask_b32_e32 v139, v139, v140, vcc
	v_cmp_class_f32_e32 vcc, v138, v180
	s_nop 1
	v_cndmask_b32_e32 v138, v139, v138, vcc
	v_div_scale_f32 v139, s[0:1], v138, v138, 1.0
	v_rcp_f32_e32 v140, v139
	s_lshl_b64 s[0:1], s[8:9], 12
	s_cmp_ge_i32 s10, s16
	v_fma_f32 v141, -v139, v140, 1.0
	v_fmac_f32_e32 v140, v141, v140
	v_div_scale_f32 v141, vcc, 1.0, v138, 1.0
	v_mul_f32_e32 v142, v141, v140
	v_fma_f32 v143, -v139, v142, v141
	v_fmac_f32_e32 v142, v143, v140
	v_fma_f32 v139, -v139, v142, v141
	v_div_fmas_f32 v139, v139, v140, v142
	v_div_fixup_f32 v138, v139, v138, 1.0
	v_pk_mul_f32 v[140:141], v[118:119], v[138:139] op_sel_hi:[1,0]
	v_pk_mul_f32 v[144:145], v[102:103], v[138:139] op_sel_hi:[1,0]
	v_pk_mul_f32 v[154:155], v[104:105], v[138:139] op_sel_hi:[1,0]
	v_pk_mul_f32 v[156:157], v[98:99], v[138:139] op_sel_hi:[1,0]
	v_pk_mul_f32 v[158:159], v[100:101], v[138:139] op_sel_hi:[1,0]
	v_pk_mul_f32 v[162:163], v[116:117], v[138:139] op_sel_hi:[1,0]
	v_pk_mul_f32 v[164:165], v[106:107], v[138:139] op_sel_hi:[1,0]
	v_pk_mul_f32 v[166:167], v[108:109], v[138:139] op_sel_hi:[1,0]
	ds_read_b128 v[98:101], v131
	ds_read_b128 v[102:105], v192
	ds_read_b128 v[106:109], v193
	ds_read_b128 v[116:119], v194
	v_pk_mul_f32 v[120:121], v[120:121], v[138:139] op_sel_hi:[1,0]
	v_pk_mul_f32 v[110:111], v[110:111], v[138:139] op_sel_hi:[1,0]
	v_pk_mul_f32 v[142:143], v[112:113], v[138:139] op_sel_hi:[1,0]
	v_pk_mul_f32 v[160:161], v[114:115], v[138:139] op_sel_hi:[1,0]
	v_pk_mul_f32 v[168:169], v[126:127], v[138:139] op_sel_hi:[1,0]
	v_pk_mul_f32 v[174:175], v[124:125], v[138:139] op_sel_hi:[1,0]
	s_waitcnt lgkmcnt(2)
	v_pk_fma_f32 v[114:115], v[100:101], v[120:121], v[104:105]
	v_pk_fma_f32 v[112:113], v[98:99], v[140:141], v[102:103]
	s_waitcnt lgkmcnt(0)
	v_pk_fma_f32 v[118:119], v[108:109], v[142:143], v[118:119]
	v_pk_fma_f32 v[116:117], v[106:107], v[110:111], v[116:117]
	ds_read_b128 v[98:101], v195
	ds_read_b128 v[102:105], v196
	ds_read_b128 v[106:109], v197
	ds_read_b128 v[124:127], v198
	ds_read_b128 v[140:143], v199
	ds_read_b128 v[148:151], v200
	v_pk_mul_f32 v[170:171], v[128:129], v[138:139] op_sel_hi:[1,0]
	v_pk_mul_f32 v[172:173], v[122:123], v[138:139] op_sel_hi:[1,0]
	s_waitcnt lgkmcnt(4)
	v_pk_fma_f32 v[122:123], v[100:101], v[154:155], v[104:105]
	v_pk_fma_f32 v[120:121], v[98:99], v[144:145], v[102:103]
	s_waitcnt lgkmcnt(2)
	v_pk_fma_f32 v[126:127], v[108:109], v[158:159], v[126:127]
	v_pk_fma_f32 v[124:125], v[106:107], v[156:157], v[124:125]
	s_waitcnt lgkmcnt(0)
	v_pk_fma_f32 v[138:139], v[142:143], v[162:163], v[150:151]
	v_pk_fma_f32 v[128:129], v[140:141], v[160:161], v[148:149]
	ds_read_b128 v[98:101], v201
	ds_read_b128 v[102:105], v202
	ds_read_b128 v[106:109], v203
	ds_read_b128 v[148:151], v204
	ds_read_b128 v[154:157], v205
	ds_read_b128 v[158:161], v206
	s_waitcnt lgkmcnt(4)
; #define LAS __attribute__((address_space(3)))
; __device__ __forceinline__ unsigned pk2(float lo, float hi) { return f2bf(lo) | (f2bf(hi) << 16); }
; __device__ __forceinline__ void ln_norm_only(f32x4 (&v)[8]) {
;     float s = 0.f;
; #pragma unroll
;     for (int j = 0; j < 8; ++j) s += (v[j][0] + v[j][1]) + (v[j][2] + v[j][3]);
;     const float mean = wave_sum(s) * (1.0f / DM); float q = 0.f;
; __device__ __forceinline__ void ln1_router(Frame& F, int l, int nrows) {
;     ...
; #pragma unroll
;             for (int j = 0; j < 8; ++j) { const int cc = 256 * j + 4 * F.lane; v[q][j] = v[q][j] * *(const LAS f32x4*)(PWS + cc) + *(const LAS f32x4*)(PBS + cc); }
;             if (q == 0 || has1) { bf16* xo = XM + (size_t)row * DM;
; #pragma unroll
;                 for (int j = 0; j < 8; ++j) { v2u w; w.x = pk2(v[q][j][0], v[q][j][1]); w.y = pk2(v[q][j][2], v[q][j][3]); *(v2u*)(xo + 256 * j + 4 * F.lane) = w; } }
	v_pk_fma_f32 v[140:141], v[98:99], v[164:165], v[102:103]
	v_bfe_u32 v98, v112, 16, 1
	v_add3_u32 v98, v112, v98, s70
	v_bfe_u32 v99, v113, 16, 1
	v_lshrrev_b32_e32 v98, 16, v98
	v_add3_u32 v99, v113, v99, s70
	v_pk_fma_f32 v[142:143], v[100:101], v[166:167], v[104:105]
	v_and_or_b32 v100, v99, s33, v98
	v_bfe_u32 v98, v114, 16, 1
	v_add3_u32 v98, v114, v98, s70
	v_bfe_u32 v99, v115, 16, 1
	v_lshrrev_b32_e32 v98, 16, v98
	v_add3_u32 v99, v115, v99, s70
	v_and_or_b32 v101, v99, s33, v98
	v_lshl_add_u64 v[98:99], v[136:137], 0, s[0:1]
	global_store_dwordx2 v[98:99], v[100:101], off
	v_bfe_u32 v100, v116, 16, 1
	v_add3_u32 v100, v116, v100, s70
	v_bfe_u32 v101, v117, 16, 1
	v_lshrrev_b32_e32 v100, 16, v100
	v_add3_u32 v101, v117, v101, s70
	v_and_or_b32 v100, v101, s33, v100
	v_bfe_u32 v101, v118, 16, 1
	v_add3_u32 v101, v118, v101, s70
	v_bfe_u32 v102, v119, 16, 1
	v_lshrrev_b32_e32 v101, 16, v101
	v_add3_u32 v102, v119, v102, s70
	v_and_or_b32 v101, v102, s33, v101
	global_store_dwordx2 v[98:99], v[100:101], off offset:512
	v_bfe_u32 v100, v120, 16, 1
	v_add3_u32 v100, v120, v100, s70
	v_bfe_u32 v101, v121, 16, 1
	v_lshrrev_b32_e32 v100, 16, v100
	v_add3_u32 v101, v121, v101, s70
	v_and_or_b32 v100, v101, s33, v100
	v_bfe_u32 v101, v122, 16, 1
	v_add3_u32 v101, v122, v101, s70
	v_bfe_u32 v102, v123, 16, 1
	v_lshrrev_b32_e32 v101, 16, v101
	v_add3_u32 v102, v123, v102, s70
	v_and_or_b32 v101, v102, s33, v101
	global_store_dwordx2 v[98:99], v[100:101], off offset:1024
	v_bfe_u32 v100, v124, 16, 1
	v_add3_u32 v100, v124, v100, s70
	v_bfe_u32 v101, v125, 16, 1
	v_lshrrev_b32_e32 v100, 16, v100
	v_add3_u32 v101, v125, v101, s70
	v_and_or_b32 v100, v101, s33, v100
	v_bfe_u32 v101, v126, 16, 1
	v_add3_u32 v101, v126, v101, s70
	v_bfe_u32 v102, v127, 16, 1
	v_lshrrev_b32_e32 v101, 16, v101
	v_add3_u32 v102, v127, v102, s70
	v_and_or_b32 v101, v102, s33, v101
	v_mov_b32_e32 v102, v66
	v_mov_b32_e32 v103, v70
	v_mov_b32_e32 v144, v67
	v_mov_b32_e32 v145, v71
	s_waitcnt lgkmcnt(2)
	v_pk_fma_f32 v[110:111], v[108:109], v[170:171], v[150:151]
	v_pk_fma_f32 v[108:109], v[106:107], v[168:169], v[148:149]
	v_pk_add_f32 v[102:103], v[102:103], v[144:145]
	v_mov_b32_e32 v144, v68
	v_mov_b32_e32 v145, v72
	v_mov_b32_e32 v148, v69
	v_mov_b32_e32 v149, v73
	v_pk_add_f32 v[144:145], v[144:145], v[148:149]
	v_mov_b32_e32 v148, v74
	v_pk_add_f32 v[102:103], v[102:103], v[144:145]
	v_mov_b32_e32 v144, v75
	v_mov_b32_e32 v145, v76
	v_mov_b32_e32 v149, v77
	v_pk_add_f32 v[144:145], v[144:145], v[148:149]
	v_add_f32_e32 v102, 0, v102
	v_pk_add_f32 v[144:145], v[144:145], v[144:145] op_sel:[0,1] op_sel_hi:[1,0]
	v_add_f32_e32 v102, v102, v103
	v_add_f32_e32 v148, v78, v79
	v_add_f32_e32 v150, v80, v81
	v_mov_b32_e32 v103, v86
	v_mov_b32_e32 v145, v87
	v_mov_b32_e32 v149, v88
	v_mov_b32_e32 v151, v89
	v_pk_add_f32 v[102:103], v[102:103], v[144:145]
	v_pk_add_f32 v[144:145], v[148:149], v[150:151]
	v_mov_b32_e32 v148, v90
	v_pk_add_f32 v[102:103], v[102:103], v[144:145]
	v_mov_b32_e32 v144, v91
	v_mov_b32_e32 v145, v92
	v_mov_b32_e32 v149, v93
	v_pk_add_f32 v[144:145], v[144:145], v[148:149]
	v_pk_add_f32 v[102:103], v[102:103], v[102:103] op_sel:[0,1] op_sel_hi:[1,0]
	v_pk_add_f32 v[144:145], v[144:145], v[144:145] op_sel:[0,1] op_sel_hi:[1,0]
	v_add_f32_e32 v148, v94, v95
	v_add_f32_e32 v150, v96, v97
	v_mov_b32_e32 v103, v82
	v_mov_b32_e32 v145, v83
	v_mov_b32_e32 v149, v84
	v_mov_b32_e32 v151, v85
	v_pk_add_f32 v[102:103], v[102:103], v[144:145]
	v_pk_add_f32 v[144:145], v[148:149], v[150:151]
	global_store_dwordx2 v[98:99], v[100:101], off offset:1536
	v_pk_add_f32 v[102:103], v[102:103], v[144:145]
	v_bfe_u32 v100, v128, 16, 1
	v_add_f32_e32 v102, v102, v103
	s_nop 1
	v_mov_b32_dpp v103, v102 quad_perm:[1,0,3,2] row_mask:0xf bank_mask:0xf
	v_add3_u32 v100, v128, v100, s70
	v_lshrrev_b32_e32 v100, 16, v100
	v_bfe_u32 v144, v139, 16, 1
	v_add3_u32 v144, v139, v144, s70
	s_waitcnt lgkmcnt(0)
	v_add_f32_e32 v101, v102, v103
	s_nop 1
	v_mov_b32_dpp v102, v101 quad_perm:[2,3,0,1] row_mask:0xf bank_mask:0xf
	v_bfe_u32 v103, v129, 16, 1
	v_add3_u32 v103, v129, v103, s70
	v_and_or_b32 v100, v103, s33, v100
	v_bfe_u32 v103, v138, 16, 1
	s_waitcnt lgkmcnt(0)
	v_add_f32_e32 v101, v101, v102
	s_nop 1
	v_mov_b32_dpp v102, v101 row_half_mirror row_mask:0xf bank_mask:0xf
	s_nop 1
	v_mov_b32_dpp v102, v102 quad_perm:[3,2,1,0] row_mask:0xf bank_mask:0xf
	v_add3_u32 v103, v138, v103, s70
	v_lshrrev_b32_e32 v103, 16, v103
	v_pk_fma_f32 v[106:107], v[154:155], v[172:173], v[158:159]
	v_bfe_u32 v155, v143, 16, 1
	s_waitcnt lgkmcnt(0)
	v_add_f32_e32 v102, v101, v102
	s_nop 1
	v_mov_b32_dpp v145, v102 row_ror:8 row_mask:0xf bank_mask:0xf
	v_and_or_b32 v101, v144, s33, v103
	global_store_dwordx2 v[98:99], v[100:101], off offset:2048
	v_bfe_u32 v100, v140, 16, 1
	v_add3_u32 v100, v140, v100, s70
	s_waitcnt lgkmcnt(0)
	v_add_f32_e32 v101, v102, v145
	v_mov_b32_e32 v102, v101
	s_nop 1
	v_permlane16_swap_b32_e32 v101, v102
	v_bfe_u32 v103, v141, 16, 1
	v_lshrrev_b32_e32 v100, 16, v100
	v_add3_u32 v103, v141, v103, s70
	v_and_or_b32 v100, v103, s33, v100
	s_waitcnt lgkmcnt(0)
	v_add_f32_e32 v101, v101, v102
	v_mov_b32_e32 v102, v101
	s_nop 1
	v_permlane32_swap_b32_e32 v101, v102
	v_bfe_u32 v103, v142, 16, 1
	v_add3_u32 v103, v142, v103, s70
	v_lshrrev_b32_e32 v154, 16, v103
	v_pk_fma_f32 v[104:105], v[156:157], v[174:175], v[160:161]
	s_waitcnt lgkmcnt(0)
; #define LAS __attribute__((address_space(3)))
; __device__ __forceinline__ unsigned pk2(float lo, float hi) { return f2bf(lo) | (f2bf(hi) << 16); }
; __device__ __forceinline__ void ln_norm_only(f32x4 (&v)[8]) {
;     ...
;     const float mean = wave_sum(s) * (1.0f / DM); float q = 0.f;
; #pragma unroll
;     for (int j = 0; j < 8; ++j) { v[j] = v[j] - mean; q += (v[j][0] * v[j][0] + v[j][1] * v[j][1]) + (v[j][2] * v[j][2] + v[j][3] * v[j][3]); }
;     const float rstd = 1.0f / sqrtf(wave_sum(q) * (1.0f / DM) + LN_EPS);
; #pragma unroll
;     for (int j = 0; j < 8; ++j) v[j] = v[j] * rstd;
; }
; __device__ __forceinline__ void ln1_router(Frame& F, int l, int nrows) {
;     ...
; #pragma unroll
;             for (int j = 0; j < 8; ++j) { const int cc = 256 * j + 4 * F.lane; v[q][j] = v[q][j] * *(const LAS f32x4*)(PWS + cc) + *(const LAS f32x4*)(PBS + cc); }
;             if (q == 0 || has1) { bf16* xo = XM + (size_t)row * DM;
; #pragma unroll
;                 for (int j = 0; j < 8; ++j) { v2u w; w.x = pk2(v[q][j][0], v[q][j][1]); w.y = pk2(v[q][j][2], v[q][j][3]); *(v2u*)(xo + 256 * j + 4 * F.lane) = w; } }
	v_add_f32_e32 v101, v101, v102
	v_fmamk_f32 v67, v101, 0xba000000, v67
	v_fmamk_f32 v71, v101, 0xba000000, v71
	v_fmamk_f32 v69, v101, 0xba000000, v69
	v_fmac_f32_e32 v66, 0xba000000, v101
	v_fmamk_f32 v73, v101, 0xba000000, v73
	v_fmac_f32_e32 v70, 0xba000000, v101
	v_mov_b32_e32 v144, v67
	v_mov_b32_e32 v145, v71
	v_fmamk_f32 v68, v101, 0xba000000, v68
	v_fmamk_f32 v72, v101, 0xba000000, v72
	v_mov_b32_e32 v102, v66
	v_mov_b32_e32 v103, v70
	v_pk_mul_f32 v[144:145], v[144:145], v[144:145]
	v_mov_b32_e32 v148, v69
	v_mov_b32_e32 v149, v73
	v_pk_fma_f32 v[102:103], v[102:103], v[102:103], v[144:145]
	v_mov_b32_e32 v144, v68
	v_mov_b32_e32 v145, v72
	v_pk_mul_f32 v[148:149], v[148:149], v[148:149]
	v_fmamk_f32 v75, v101, 0xba000000, v75
	v_pk_fma_f32 v[144:145], v[144:145], v[144:145], v[148:149]
	v_fmamk_f32 v74, v101, 0xba000000, v74
	v_pk_add_f32 v[102:103], v[102:103], v[144:145]
	v_fmamk_f32 v77, v101, 0xba000000, v77
	v_fmac_f32_e32 v76, 0xba000000, v101
	v_pk_add_f32 v[102:103], v[102:103], v[102:103] op_sel_hi:[0,1]
	v_pk_mul_f32 v[144:145], v[76:77], v[76:77]
	v_pk_mul_f32 v[148:149], v[74:75], v[74:75]
	v_fmamk_f32 v78, v101, 0xba000000, v78
	v_pk_mov_b32 v[150:151], v[148:149], v[144:145] op_sel:[1,0]
	v_mov_b32_e32 v149, v145
	v_fmamk_f32 v79, v101, 0xba000000, v79
	v_fmac_f32_e32 v80, 0xba000000, v101
	v_mul_f32_e32 v102, v78, v78
	v_pk_add_f32 v[144:145], v[150:151], v[148:149]
	v_fmamk_f32 v81, v101, 0xba000000, v81
	v_pk_fma_f32 v[148:149], v[78:79], v[78:79], v[102:103] op_sel_hi:[1,1,0]
	v_mul_f32_e32 v102, v80, v80
	v_pk_add_f32 v[144:145], v[144:145], v[144:145] op_sel_hi:[0,1]
	v_pk_fma_f32 v[150:151], v[80:81], v[80:81], v[102:103] op_sel_hi:[1,1,0]
	v_fmamk_f32 v89, v101, 0xba000000, v89
	v_fmamk_f32 v88, v101, 0xba000000, v88
	v_fmamk_f32 v87, v101, 0xba000000, v87
	v_fmac_f32_e32 v86, 0xba000000, v101
	v_mul_f32_e32 v148, v86, v86
	v_mul_f32_e32 v150, v87, v87
	v_mul_f32_e32 v144, v88, v88
	v_mul_f32_e32 v102, v89, v89
	v_pk_add_f32 v[148:149], v[148:149], v[150:151]
	v_pk_add_f32 v[102:103], v[144:145], v[102:103]
	v_fmamk_f32 v91, v101, 0xba000000, v91
	v_pk_add_f32 v[102:103], v[148:149], v[102:103]
	v_fmamk_f32 v90, v101, 0xba000000, v90
	v_fmamk_f32 v93, v101, 0xba000000, v93
	v_fmac_f32_e32 v92, 0xba000000, v101
	v_pk_add_f32 v[102:103], v[102:103], v[102:103] op_sel_hi:[0,1]
	v_pk_mul_f32 v[144:145], v[92:93], v[92:93]
	v_pk_mul_f32 v[148:149], v[90:91], v[90:91]
	v_fmamk_f32 v94, v101, 0xba000000, v94
	v_pk_mov_b32 v[150:151], v[148:149], v[144:145] op_sel:[1,0]
	v_mov_b32_e32 v149, v145
	v_fmamk_f32 v95, v101, 0xba000000, v95
	v_fmac_f32_e32 v96, 0xba000000, v101
	v_mul_f32_e32 v102, v94, v94
	v_pk_add_f32 v[144:145], v[150:151], v[148:149]
	v_fmamk_f32 v97, v101, 0xba000000, v97
	v_pk_fma_f32 v[148:149], v[94:95], v[94:95], v[102:103] op_sel_hi:[1,1,0]
	v_mul_f32_e32 v102, v96, v96
	v_pk_add_f32 v[144:145], v[144:145], v[144:145] op_sel_hi:[0,1]
	v_pk_fma_f32 v[150:151], v[96:97], v[96:97], v[102:103] op_sel_hi:[1,1,0]
	v_fmamk_f32 v85, v101, 0xba000000, v85
	v_fmamk_f32 v84, v101, 0xba000000, v84
	v_fmamk_f32 v83, v101, 0xba000000, v83
	v_fmac_f32_e32 v82, 0xba000000, v101
	v_mul_f32_e32 v148, v82, v82
	v_mul_f32_e32 v150, v83, v83
	v_mul_f32_e32 v144, v84, v84
	v_mul_f32_e32 v102, v85, v85
	v_pk_add_f32 v[148:149], v[148:149], v[150:151]
	v_pk_add_f32 v[102:103], v[144:145], v[102:103]
	v_add3_u32 v101, v143, v155, s70
	v_pk_add_f32 v[102:103], v[148:149], v[102:103]
	v_and_or_b32 v101, v101, s33, v154
	v_add_f32_e32 v102, v102, v103
	s_nop 1
	v_mov_b32_dpp v103, v102 quad_perm:[1,0,3,2] row_mask:0xf bank_mask:0xf
	global_store_dwordx2 v[98:99], v[100:101], off offset:2560
	v_bfe_u32 v100, v108, 16, 1
	v_add3_u32 v100, v108, v100, s70
	v_lshrrev_b32_e32 v100, 16, v100
	s_waitcnt lgkmcnt(0)
	v_add_f32_e32 v101, v102, v103
	s_nop 1
	v_mov_b32_dpp v102, v101 quad_perm:[2,3,0,1] row_mask:0xf bank_mask:0xf
	v_bfe_u32 v103, v109, 16, 1
	v_add3_u32 v103, v109, v103, s70
	v_and_or_b32 v100, v103, s33, v100
	v_bfe_u32 v103, v110, 16, 1
	s_waitcnt lgkmcnt(0)
	v_add_f32_e32 v101, v101, v102
	s_nop 1
	v_mov_b32_dpp v102, v101 row_half_mirror row_mask:0xf bank_mask:0xf
	s_nop 1
	v_mov_b32_dpp v102, v102 quad_perm:[3,2,1,0] row_mask:0xf bank_mask:0xf
	v_add3_u32 v103, v110, v103, s70
	v_lshrrev_b32_e32 v103, 16, v103
	s_waitcnt lgkmcnt(0)
	v_add_f32_e32 v102, v101, v102
	s_nop 1
	v_mov_b32_dpp v144, v102 row_ror:8 row_mask:0xf bank_mask:0xf
	v_bfe_u32 v101, v111, 16, 1
	v_add3_u32 v101, v111, v101, s70
	v_and_or_b32 v101, v101, s33, v103
	global_store_dwordx2 v[98:99], v[100:101], off offset:3072
	s_waitcnt lgkmcnt(0)
	v_add_f32_e32 v100, v102, v144
	v_mov_b32_e32 v101, v100
	s_nop 1
	v_permlane16_swap_b32_e32 v100, v101
	v_bfe_u32 v103, v107, 16, 1
	v_bfe_u32 v102, v106, 16, 1
	v_add3_u32 v102, v106, v102, s70
	v_lshrrev_b32_e32 v102, 16, v102
	s_waitcnt lgkmcnt(0)
	v_add_f32_e32 v101, v100, v101
	v_mov_b32_e32 v144, v101
	s_nop 1
	v_permlane32_swap_b32_e32 v101, v144
	v_add3_u32 v100, v107, v103, s70
	v_and_or_b32 v100, v100, s33, v102
	v_bfe_u32 v102, v104, 16, 1
	v_add3_u32 v102, v104, v102, s70
	s_waitcnt lgkmcnt(0)
; #define LAS __attribute__((address_space(3)))
; __device__ __forceinline__ unsigned pk2(float lo, float hi) { return f2bf(lo) | (f2bf(hi) << 16); }
; __device__ __forceinline__ void ln_norm_only(f32x4 (&v)[8]) {
;     ...
;     const float rstd = 1.0f / sqrtf(wave_sum(q) * (1.0f / DM) + LN_EPS);
; #pragma unroll
;     for (int j = 0; j < 8; ++j) v[j] = v[j] * rstd;
; __device__ __forceinline__ void ln1_router(Frame& F, int l, int nrows) {
;     ...
;         for (int q = 0; q < 2; ++q) { const int row = rows[q];
;             ln_norm_only(v[q]);
; #pragma unroll
;             for (int j = 0; j < 8; ++j) { const int cc = 256 * j + 4 * F.lane; v[q][j] = v[q][j] * *(const LAS f32x4*)(PWS + cc) + *(const LAS f32x4*)(PBS + cc); }
;             if (q == 0 || has1) { bf16* xo = XM + (size_t)row * DM;
; #pragma unroll
;                 for (int j = 0; j < 8; ++j) { v2u w; w.x = pk2(v[q][j][0], v[q][j][1]); w.y = pk2(v[q][j][2], v[q][j][3]); *(v2u*)(xo + 256 * j + 4 * F.lane) = w; } }
;             asm volatile("" ::: "memory"); }
	v_add_f32_e32 v101, v101, v144
	v_fmamk_f32 v101, v101, 0x3a000000, v179
	v_mul_f32_e32 v103, 0x4f800000, v101
	v_cmp_gt_f32_e32 vcc, s11, v101
	v_bfe_u32 v144, v105, 16, 1
	v_lshrrev_b32_e32 v102, 16, v102
	v_cndmask_b32_e32 v101, v101, v103, vcc
	v_sqrt_f32_e32 v103, v101
	v_add3_u32 v144, v105, v144, s70
	v_add_u32_e32 v145, -1, v103
	v_fma_f32 v148, -v145, v103, v101
	v_cmp_ge_f32_e64 s[0:1], 0, v148
	v_add_u32_e32 v148, 1, v103
	s_nop 0
	v_cndmask_b32_e64 v145, v103, v145, s[0:1]
	v_fma_f32 v103, -v148, v103, v101
	v_cmp_lt_f32_e64 s[0:1], 0, v103
	s_nop 1
	v_cndmask_b32_e64 v103, v145, v148, s[0:1]
	v_mul_f32_e32 v145, 0x37800000, v103
	v_cndmask_b32_e32 v103, v103, v145, vcc
	v_cmp_class_f32_e32 vcc, v101, v180
	s_nop 1
	v_cndmask_b32_e32 v103, v103, v101, vcc
	v_div_scale_f32 v145, s[0:1], v103, v103, 1.0
	v_rcp_f32_e32 v148, v145
	v_and_or_b32 v101, v144, s33, v102
	global_store_dwordx2 v[98:99], v[100:101], off offset:3584
	v_fma_f32 v98, -v145, v148, 1.0
	v_fmac_f32_e32 v148, v98, v148
	v_div_scale_f32 v98, vcc, 1.0, v103, 1.0
	v_mul_f32_e32 v99, v98, v148
	v_fma_f32 v100, -v145, v99, v98
	v_fmac_f32_e32 v99, v100, v148
	v_fma_f32 v98, -v145, v99, v98
	v_div_fmas_f32 v98, v98, v148, v99
	v_div_fixup_f32 v98, v98, v103, 1.0
	v_pk_mul_f32 v[100:101], v[68:69], v[98:99] op_sel_hi:[1,0]
	v_pk_mul_f32 v[102:103], v[66:67], v[98:99] op_sel_hi:[1,0]
	v_pk_mul_f32 v[144:145], v[72:73], v[98:99] op_sel_hi:[1,0]
	v_pk_mul_f32 v[148:149], v[70:71], v[98:99] op_sel_hi:[1,0]
	v_pk_mul_f32 v[150:151], v[76:77], v[98:99] op_sel_hi:[1,0]
	v_pk_mul_f32 v[154:155], v[74:75], v[98:99] op_sel_hi:[1,0]
	v_pk_mul_f32 v[156:157], v[80:81], v[98:99] op_sel_hi:[1,0]
	v_pk_mul_f32 v[158:159], v[78:79], v[98:99] op_sel_hi:[1,0]
	ds_read_b128 v[66:69], v131
	ds_read_b128 v[70:73], v192
	ds_read_b128 v[74:77], v193
	ds_read_b128 v[78:81], v194
	v_pk_mul_f32 v[160:161], v[88:89], v[98:99] op_sel_hi:[1,0]
	v_pk_mul_f32 v[162:163], v[86:87], v[98:99] op_sel_hi:[1,0]
	v_pk_mul_f32 v[164:165], v[92:93], v[98:99] op_sel_hi:[1,0]
	v_pk_mul_f32 v[166:167], v[90:91], v[98:99] op_sel_hi:[1,0]
	v_pk_mul_f32 v[168:169], v[96:97], v[98:99] op_sel_hi:[1,0]
	v_pk_mul_f32 v[170:171], v[94:95], v[98:99] op_sel_hi:[1,0]
	v_pk_mul_f32 v[172:173], v[84:85], v[98:99] op_sel_hi:[1,0]
	v_pk_mul_f32 v[174:175], v[82:83], v[98:99] op_sel_hi:[1,0]
	s_waitcnt lgkmcnt(2)
	v_pk_fma_f32 v[70:71], v[66:67], v[102:103], v[70:71]
	v_pk_fma_f32 v[72:73], v[68:69], v[100:101], v[72:73]
	s_waitcnt lgkmcnt(0)
	v_pk_fma_f32 v[74:75], v[74:75], v[148:149], v[78:79]
	v_pk_fma_f32 v[76:77], v[76:77], v[144:145], v[80:81]
	ds_read_b128 v[66:69], v195
	ds_read_b128 v[78:81], v196
	ds_read_b128 v[82:85], v197
	ds_read_b128 v[86:89], v198
	ds_read_b128 v[90:93], v199
	ds_read_b128 v[94:97], v200
	s_waitcnt lgkmcnt(4)
	v_pk_fma_f32 v[78:79], v[66:67], v[154:155], v[78:79]
	v_pk_fma_f32 v[80:81], v[68:69], v[150:151], v[80:81]
	s_waitcnt lgkmcnt(2)
	v_pk_fma_f32 v[82:83], v[82:83], v[158:159], v[86:87]
	v_pk_fma_f32 v[84:85], v[84:85], v[156:157], v[88:89]
	s_waitcnt lgkmcnt(0)
	v_pk_fma_f32 v[86:87], v[90:91], v[162:163], v[94:95]
	v_pk_fma_f32 v[88:89], v[92:93], v[160:161], v[96:97]
	ds_read_b128 v[66:69], v201
	ds_read_b128 v[90:93], v202
	ds_read_b128 v[94:97], v203
	ds_read_b128 v[98:101], v204
	ds_read_b128 v[148:151], v205
	ds_read_b128 v[154:157], v206
	s_waitcnt lgkmcnt(4)
	v_pk_fma_f32 v[90:91], v[66:67], v[166:167], v[90:91]
	v_pk_fma_f32 v[92:93], v[68:69], v[164:165], v[92:93]
	s_waitcnt lgkmcnt(2)
	v_pk_fma_f32 v[94:95], v[94:95], v[170:171], v[98:99]
	v_pk_fma_f32 v[96:97], v[96:97], v[168:169], v[100:101]
	s_waitcnt lgkmcnt(0)
	v_pk_fma_f32 v[98:99], v[148:149], v[174:175], v[154:155]
	v_pk_fma_f32 v[100:101], v[150:151], v[172:173], v[156:157]
	s_cbranch_scc1 .LBB0_1318
; __device__ __forceinline__ unsigned pk2(float lo, float hi) { return f2bf(lo) | (f2bf(hi) << 16); }
; __device__ __forceinline__ void ln1_router(Frame& F, int l, int nrows) {
;     ...
;             if (q == 0 || has1) { bf16* xo = XM + (size_t)row * DM;
; #pragma unroll
;                 for (int j = 0; j < 8; ++j) { v2u w; w.x = pk2(v[q][j][0], v[q][j][1]); w.y = pk2(v[q][j][2], v[q][j][3]); *(v2u*)(xo + 256 * j + 4 * F.lane) = w; } }
	v_bfe_u32 v66, v70, 16, 1
	v_add3_u32 v66, v70, v66, s70
	v_bfe_u32 v67, v71, 16, 1
	v_lshrrev_b32_e32 v66, 16, v66
	v_add3_u32 v67, v71, v67, s70
	v_and_or_b32 v66, v67, s33, v66
	v_bfe_u32 v67, v72, 16, 1
	s_ashr_i32 s11, s10, 31
	v_add3_u32 v67, v72, v67, s70
	v_bfe_u32 v68, v73, 16, 1
	s_lshl_b64 s[0:1], s[10:11], 12
	v_lshrrev_b32_e32 v67, 16, v67
	v_add3_u32 v68, v73, v68, s70
	v_and_or_b32 v67, v68, s33, v67
	v_lshl_add_u64 v[68:69], v[136:137], 0, s[0:1]
	global_store_dwordx2 v[68:69], v[66:67], off
	v_bfe_u32 v66, v74, 16, 1
	v_add3_u32 v66, v74, v66, s70
	v_bfe_u32 v67, v75, 16, 1
	v_lshrrev_b32_e32 v66, 16, v66
	v_add3_u32 v67, v75, v67, s70
	v_and_or_b32 v66, v67, s33, v66
	v_bfe_u32 v67, v76, 16, 1
	v_add3_u32 v67, v76, v67, s70
	v_bfe_u32 v102, v77, 16, 1
	v_lshrrev_b32_e32 v67, 16, v67
	v_add3_u32 v102, v77, v102, s70
	v_and_or_b32 v67, v102, s33, v67
	global_store_dwordx2 v[68:69], v[66:67], off offset:512
	v_bfe_u32 v66, v78, 16, 1
	v_add3_u32 v66, v78, v66, s70
	v_bfe_u32 v67, v79, 16, 1
	v_lshrrev_b32_e32 v66, 16, v66
	v_add3_u32 v67, v79, v67, s70
	v_and_or_b32 v66, v67, s33, v66
	v_bfe_u32 v67, v80, 16, 1
	v_add3_u32 v67, v80, v67, s70
	v_bfe_u32 v102, v81, 16, 1
	v_lshrrev_b32_e32 v67, 16, v67
	v_add3_u32 v102, v81, v102, s70
	v_and_or_b32 v67, v102, s33, v67
	global_store_dwordx2 v[68:69], v[66:67], off offset:1024
	v_bfe_u32 v66, v82, 16, 1
	v_add3_u32 v66, v82, v66, s70
	v_bfe_u32 v67, v83, 16, 1
	v_lshrrev_b32_e32 v66, 16, v66
	v_add3_u32 v67, v83, v67, s70
	v_and_or_b32 v66, v67, s33, v66
	v_bfe_u32 v67, v84, 16, 1
	v_add3_u32 v67, v84, v67, s70
	v_bfe_u32 v102, v85, 16, 1
	v_lshrrev_b32_e32 v67, 16, v67
	v_add3_u32 v102, v85, v102, s70
	v_and_or_b32 v67, v102, s33, v67
	global_store_dwordx2 v[68:69], v[66:67], off offset:1536
	v_bfe_u32 v66, v86, 16, 1
	v_add3_u32 v66, v86, v66, s70
	v_bfe_u32 v67, v87, 16, 1
	v_lshrrev_b32_e32 v66, 16, v66
	v_add3_u32 v67, v87, v67, s70
	v_and_or_b32 v66, v67, s33, v66
	v_bfe_u32 v67, v88, 16, 1
	v_add3_u32 v67, v88, v67, s70
	v_bfe_u32 v102, v89, 16, 1
	v_lshrrev_b32_e32 v67, 16, v67
	v_add3_u32 v102, v89, v102, s70
	v_and_or_b32 v67, v102, s33, v67
	global_store_dwordx2 v[68:69], v[66:67], off offset:2048
	v_bfe_u32 v66, v90, 16, 1
	v_add3_u32 v66, v90, v66, s70
	v_bfe_u32 v67, v91, 16, 1
	v_lshrrev_b32_e32 v66, 16, v66
	v_add3_u32 v67, v91, v67, s70
	v_and_or_b32 v66, v67, s33, v66
	v_bfe_u32 v67, v92, 16, 1
	v_add3_u32 v67, v92, v67, s70
	v_bfe_u32 v102, v93, 16, 1
	v_lshrrev_b32_e32 v67, 16, v67
	v_add3_u32 v102, v93, v102, s70
	v_and_or_b32 v67, v102, s33, v67
	global_store_dwordx2 v[68:69], v[66:67], off offset:2560
	v_bfe_u32 v66, v94, 16, 1
	v_add3_u32 v66, v94, v66, s70
	v_bfe_u32 v67, v95, 16, 1
	v_lshrrev_b32_e32 v66, 16, v66
	v_add3_u32 v67, v95, v67, s70
	v_and_or_b32 v66, v67, s33, v66
	v_bfe_u32 v67, v96, 16, 1
	v_add3_u32 v67, v96, v67, s70
	v_bfe_u32 v102, v97, 16, 1
	v_lshrrev_b32_e32 v67, 16, v67
	v_add3_u32 v102, v97, v102, s70
	v_and_or_b32 v67, v102, s33, v67
	global_store_dwordx2 v[68:69], v[66:67], off offset:3072
	v_bfe_u32 v66, v98, 16, 1
	v_add3_u32 v66, v98, v66, s70
	v_bfe_u32 v67, v99, 16, 1
	v_lshrrev_b32_e32 v66, 16, v66
	v_add3_u32 v67, v99, v67, s70
	v_and_or_b32 v66, v67, s33, v66
	v_bfe_u32 v67, v100, 16, 1
	v_add3_u32 v67, v100, v67, s70
	v_bfe_u32 v102, v101, 16, 1
	v_lshrrev_b32_e32 v67, 16, v67
	v_add3_u32 v102, v101, v102, s70
	v_and_or_b32 v67, v102, s33, v67
	global_store_dwordx2 v[68:69], v[66:67], off offset:3584

; #define LAS __attribute__((address_space(3)))
; __device__ __forceinline__ void ln1_router(Frame& F, int l, int nrows) {
;     ...
;         for (int g = 0; g < 4; ++g) {
;             float a0[4], a1[4];
; #pragma unroll
;             for (int k = 0; k < 4; ++k) { float x0 = 0.f, x1 = 0.f; const LAS float* wp = RW + (4 * g + k) * DM + 4 * F.lane;
; #pragma unroll
;                 for (int j = 0; j < 8; ++j) { const f32x4 w4 = *(const LAS f32x4*)(wp + 256 * j);
;                     x0 += (v[0][j][0] * w4[0] + v[0][j][1] * w4[1]) + (v[0][j][2] * w4[2] + v[0][j][3] * w4[3]);
;                     x1 += (v[1][j][0] * w4[0] + v[1][j][1] * w4[1]) + (v[1][j][2] * w4[2] + v[1][j][3] * w4[3]); }
;                 a0[k] = x0; a1[k] = x1; }
.LBB0_1319:
	v_add_u32_e32 v66, s0, v207
	ds_read_b128 v[142:145], v66
	ds_read_b128 v[148:151], v66 offset:1024
	ds_read_b128 v[154:157], v66 offset:2048
	ds_read_b128 v[158:161], v66 offset:3072
	ds_read_b128 v[162:165], v66 offset:4096
	ds_read_b128 v[166:169], v66 offset:5120
	s_waitcnt lgkmcnt(5)
	v_pk_mul_f32 v[68:69], v[110:111], v[142:143]
	v_cmp_eq_u32_e32 vcc, s0, v210
	v_pk_fma_f32 v[68:69], v[70:71], v[142:143], v[68:69] op_sel:[0,0,1] op_sel_hi:[1,1,0]
	v_pk_mul_f32 v[142:143], v[112:113], v[144:145]
	s_add_i32 s0, s0, 0x8000
	v_pk_fma_f32 v[142:143], v[72:73], v[144:145], v[142:143] op_sel:[0,0,1] op_sel_hi:[1,1,0]
	s_waitcnt lgkmcnt(4)
	v_pk_mul_f32 v[144:145], v[116:117], v[150:151]
	v_pk_add_f32 v[68:69], v[68:69], v[142:143]
	v_pk_mul_f32 v[142:143], v[114:115], v[148:149]
	v_pk_fma_f32 v[144:145], v[76:77], v[150:151], v[144:145] op_sel:[0,0,1] op_sel_hi:[1,1,0]
	v_pk_fma_f32 v[142:143], v[74:75], v[148:149], v[142:143] op_sel:[0,0,1] op_sel_hi:[1,1,0]
	v_pk_add_f32 v[68:69], v[68:69], 0 op_sel_hi:[1,0]
	v_pk_add_f32 v[142:143], v[142:143], v[144:145]
	s_waitcnt lgkmcnt(3)
	v_pk_mul_f32 v[144:145], v[120:121], v[156:157]
	v_pk_add_f32 v[68:69], v[68:69], v[142:143]
	v_pk_mul_f32 v[142:143], v[118:119], v[154:155]
	v_pk_fma_f32 v[144:145], v[80:81], v[156:157], v[144:145] op_sel:[0,0,1] op_sel_hi:[1,1,0]
	v_pk_fma_f32 v[142:143], v[78:79], v[154:155], v[142:143] op_sel:[0,0,1] op_sel_hi:[1,1,0]
	ds_read_b128 v[148:151], v66 offset:6144
	v_pk_add_f32 v[142:143], v[142:143], v[144:145]
	s_waitcnt lgkmcnt(3)
	v_pk_mul_f32 v[144:145], v[124:125], v[160:161]
	v_pk_add_f32 v[68:69], v[68:69], v[142:143]
	v_pk_mul_f32 v[142:143], v[122:123], v[158:159]
	v_pk_fma_f32 v[144:145], v[84:85], v[160:161], v[144:145] op_sel:[0,0,1] op_sel_hi:[1,1,0]
	v_pk_fma_f32 v[142:143], v[82:83], v[158:159], v[142:143] op_sel:[0,0,1] op_sel_hi:[1,1,0]
	s_cmp_eq_u32 s0, 0x20000
	v_pk_add_f32 v[142:143], v[142:143], v[144:145]
	s_waitcnt lgkmcnt(2)
	v_pk_mul_f32 v[144:145], v[128:129], v[164:165]
	v_pk_add_f32 v[68:69], v[68:69], v[142:143]
	v_pk_mul_f32 v[142:143], v[126:127], v[162:163]
	v_pk_fma_f32 v[144:145], v[88:89], v[164:165], v[144:145] op_sel:[0,0,1] op_sel_hi:[1,1,0]
	v_pk_fma_f32 v[142:143], v[86:87], v[162:163], v[142:143] op_sel:[0,0,1] op_sel_hi:[1,1,0]
	s_nop 0
	v_pk_add_f32 v[142:143], v[142:143], v[144:145]
	s_waitcnt lgkmcnt(1)
	v_pk_mul_f32 v[144:145], v[140:141], v[168:169]
	v_pk_add_f32 v[68:69], v[68:69], v[142:143]
	v_pk_mul_f32 v[142:143], v[138:139], v[166:167]
	v_pk_fma_f32 v[144:145], v[92:93], v[168:169], v[144:145] op_sel:[0,0,1] op_sel_hi:[1,1,0]
	v_pk_fma_f32 v[142:143], v[90:91], v[166:167], v[142:143] op_sel:[0,0,1] op_sel_hi:[1,1,0]
	s_nop 0
	v_pk_add_f32 v[142:143], v[142:143], v[144:145]
	s_waitcnt lgkmcnt(0)
	v_pk_mul_f32 v[144:145], v[108:109], v[150:151]
	v_pk_add_f32 v[142:143], v[68:69], v[142:143]
	v_pk_mul_f32 v[68:69], v[106:107], v[148:149]
	v_pk_fma_f32 v[144:145], v[96:97], v[150:151], v[144:145] op_sel:[0,0,1] op_sel_hi:[1,1,0]
	v_pk_fma_f32 v[68:69], v[94:95], v[148:149], v[68:69] op_sel:[0,0,1] op_sel_hi:[1,1,0]
	ds_read_b128 v[148:151], v66 offset:7168
	v_pk_add_f32 v[158:159], v[68:69], v[144:145]
	s_waitcnt lgkmcnt(0)
	v_pk_mul_f32 v[68:69], v[104:105], v[148:149]
	s_nop 0
	v_pk_fma_f32 v[144:145], v[98:99], v[148:149], v[68:69] op_sel:[0,0,1] op_sel_hi:[1,1,0]
	v_pk_mul_f32 v[68:69], v[102:103], v[150:151]
	v_pk_add_f32 v[142:143], v[142:143], v[158:159]
	v_pk_fma_f32 v[154:155], v[100:101], v[150:151], v[68:69] op_sel:[0,0,1] op_sel_hi:[1,1,0]
	ds_read_b128 v[148:151], v66 offset:8192
	ds_read_b128 v[160:163], v66 offset:9216
	ds_read_b128 v[164:167], v66 offset:10240
	ds_read_b128 v[168:171], v66 offset:11264
	ds_read_b128 v[172:175], v66 offset:12288
	ds_read_b128 v[186:189], v66 offset:13312
	s_waitcnt lgkmcnt(5)
	v_pk_mul_f32 v[68:69], v[110:111], v[148:149]
	v_pk_add_f32 v[144:145], v[144:145], v[154:155]
	v_pk_fma_f32 v[68:69], v[70:71], v[148:149], v[68:69] op_sel:[0,0,1] op_sel_hi:[1,1,0]
	v_pk_mul_f32 v[148:149], v[112:113], v[150:151]
	v_pk_add_f32 v[142:143], v[142:143], v[144:145]
	v_pk_fma_f32 v[148:149], v[72:73], v[150:151], v[148:149] op_sel:[0,0,1] op_sel_hi:[1,1,0]
	s_waitcnt lgkmcnt(4)
	v_pk_mul_f32 v[150:151], v[116:117], v[162:163]
	v_pk_add_f32 v[68:69], v[68:69], v[148:149]
	v_pk_mul_f32 v[148:149], v[114:115], v[160:161]
	v_pk_fma_f32 v[150:151], v[76:77], v[162:163], v[150:151] op_sel:[0,0,1] op_sel_hi:[1,1,0]
	v_pk_fma_f32 v[148:149], v[74:75], v[160:161], v[148:149] op_sel:[0,0,1] op_sel_hi:[1,1,0]
	v_pk_add_f32 v[68:69], v[68:69], 0 op_sel_hi:[1,0]
	v_pk_add_f32 v[148:149], v[148:149], v[150:151]
	s_waitcnt lgkmcnt(3)
	v_pk_mul_f32 v[150:151], v[120:121], v[166:167]
	v_pk_add_f32 v[68:69], v[68:69], v[148:149]
	v_pk_mul_f32 v[148:149], v[118:119], v[164:165]
	v_pk_fma_f32 v[150:151], v[80:81], v[166:167], v[150:151] op_sel:[0,0,1] op_sel_hi:[1,1,0]
	v_pk_fma_f32 v[148:149], v[78:79], v[164:165], v[148:149] op_sel:[0,0,1] op_sel_hi:[1,1,0]
	s_nop 0
	v_pk_add_f32 v[148:149], v[148:149], v[150:151]
	s_waitcnt lgkmcnt(2)
	v_pk_mul_f32 v[150:151], v[124:125], v[170:171]
	v_pk_add_f32 v[68:69], v[68:69], v[148:149]
	v_pk_mul_f32 v[148:149], v[122:123], v[168:169]
	v_pk_fma_f32 v[150:151], v[84:85], v[170:171], v[150:151] op_sel:[0,0,1] op_sel_hi:[1,1,0]
	v_pk_fma_f32 v[148:149], v[82:83], v[168:169], v[148:149] op_sel:[0,0,1] op_sel_hi:[1,1,0]
	s_nop 0
	v_pk_add_f32 v[148:149], v[148:149], v[150:151]
	s_waitcnt lgkmcnt(1)
; #define LAS __attribute__((address_space(3)))
; __device__ __forceinline__ void ln1_router(Frame& F, int l, int nrows) {
;     ...
;             for (int k = 0; k < 4; ++k) { float x0 = 0.f, x1 = 0.f; const LAS float* wp = RW + (4 * g + k) * DM + 4 * F.lane;
; #pragma unroll
;                 for (int j = 0; j < 8; ++j) { const f32x4 w4 = *(const LAS f32x4*)(wp + 256 * j);
;                     x0 += (v[0][j][0] * w4[0] + v[0][j][1] * w4[1]) + (v[0][j][2] * w4[2] + v[0][j][3] * w4[3]);
;                     x1 += (v[1][j][0] * w4[0] + v[1][j][1] * w4[1]) + (v[1][j][2] * w4[2] + v[1][j][3] * w4[3]); }
;                 a0[k] = x0; a1[k] = x1; }
	v_pk_mul_f32 v[150:151], v[128:129], v[174:175]
	v_pk_add_f32 v[68:69], v[68:69], v[148:149]
	v_pk_mul_f32 v[148:149], v[126:127], v[172:173]
	v_pk_fma_f32 v[150:151], v[88:89], v[174:175], v[150:151] op_sel:[0,0,1] op_sel_hi:[1,1,0]
	v_pk_fma_f32 v[148:149], v[86:87], v[172:173], v[148:149] op_sel:[0,0,1] op_sel_hi:[1,1,0]
	s_nop 0
	v_pk_add_f32 v[148:149], v[148:149], v[150:151]
	s_waitcnt lgkmcnt(0)
	v_pk_mul_f32 v[150:151], v[140:141], v[188:189]
	v_pk_add_f32 v[68:69], v[68:69], v[148:149]
	v_pk_mul_f32 v[148:149], v[138:139], v[186:187]
	v_pk_fma_f32 v[150:151], v[92:93], v[188:189], v[150:151] op_sel:[0,0,1] op_sel_hi:[1,1,0]
	v_pk_fma_f32 v[148:149], v[90:91], v[186:187], v[148:149] op_sel:[0,0,1] op_sel_hi:[1,1,0]
	s_nop 0
	v_pk_add_f32 v[148:149], v[148:149], v[150:151]
	s_nop 0
	v_pk_add_f32 v[156:157], v[68:69], v[148:149]
	ds_read_b128 v[148:151], v66 offset:14336
	s_waitcnt lgkmcnt(0)
	v_pk_mul_f32 v[68:69], v[106:107], v[148:149]
	s_nop 0
	v_pk_fma_f32 v[68:69], v[94:95], v[148:149], v[68:69] op_sel:[0,0,1] op_sel_hi:[1,1,0]
	v_pk_mul_f32 v[148:149], v[108:109], v[150:151]
	s_nop 0
	v_pk_fma_f32 v[148:149], v[96:97], v[150:151], v[148:149] op_sel:[0,0,1] op_sel_hi:[1,1,0]
	s_nop 0
	v_pk_add_f32 v[160:161], v[68:69], v[148:149]
	ds_read_b128 v[148:151], v66 offset:15360
	v_pk_add_f32 v[144:145], v[156:157], v[160:161]
	s_waitcnt lgkmcnt(0)
	v_pk_mul_f32 v[68:69], v[104:105], v[148:149]
	s_nop 0
	v_pk_fma_f32 v[162:163], v[98:99], v[148:149], v[68:69] op_sel:[0,0,1] op_sel_hi:[1,1,0]
	v_pk_mul_f32 v[68:69], v[102:103], v[150:151]
	s_nop 0
	v_pk_fma_f32 v[164:165], v[100:101], v[150:151], v[68:69] op_sel:[0,0,1] op_sel_hi:[1,1,0]
	ds_read_b128 v[148:151], v66 offset:16384
	ds_read_b128 v[166:169], v66 offset:17408
	ds_read_b128 v[170:173], v66 offset:18432
	ds_read_b128 v[174:177], v66 offset:19456
	ds_read_b128 v[186:189], v66 offset:20480
	ds_read_b128 v[218:221], v66 offset:21504
	s_waitcnt lgkmcnt(5)
	v_pk_mul_f32 v[68:69], v[110:111], v[148:149]
	s_nop 0
	v_pk_fma_f32 v[68:69], v[70:71], v[148:149], v[68:69] op_sel:[0,0,1] op_sel_hi:[1,1,0]
	v_pk_mul_f32 v[148:149], v[112:113], v[150:151]
	s_nop 0
	v_pk_fma_f32 v[148:149], v[72:73], v[150:151], v[148:149] op_sel:[0,0,1] op_sel_hi:[1,1,0]
	s_waitcnt lgkmcnt(4)
	v_pk_mul_f32 v[150:151], v[116:117], v[168:169]
	v_pk_add_f32 v[68:69], v[68:69], v[148:149]
	v_pk_mul_f32 v[148:149], v[114:115], v[166:167]
	v_pk_fma_f32 v[150:151], v[76:77], v[168:169], v[150:151] op_sel:[0,0,1] op_sel_hi:[1,1,0]
	v_pk_fma_f32 v[148:149], v[74:75], v[166:167], v[148:149] op_sel:[0,0,1] op_sel_hi:[1,1,0]
	v_pk_add_f32 v[68:69], v[68:69], 0 op_sel_hi:[1,0]
	v_pk_add_f32 v[148:149], v[148:149], v[150:151]
	s_waitcnt lgkmcnt(3)
	v_pk_mul_f32 v[150:151], v[120:121], v[172:173]
	v_pk_add_f32 v[68:69], v[68:69], v[148:149]
	v_pk_mul_f32 v[148:149], v[118:119], v[170:171]
	v_pk_fma_f32 v[150:151], v[80:81], v[172:173], v[150:151] op_sel:[0,0,1] op_sel_hi:[1,1,0]
	v_pk_fma_f32 v[148:149], v[78:79], v[170:171], v[148:149] op_sel:[0,0,1] op_sel_hi:[1,1,0]
	s_nop 0
	v_pk_add_f32 v[148:149], v[148:149], v[150:151]
	s_waitcnt lgkmcnt(2)
	v_pk_mul_f32 v[150:151], v[124:125], v[176:177]
	v_pk_add_f32 v[68:69], v[68:69], v[148:149]
	v_pk_mul_f32 v[148:149], v[122:123], v[174:175]
	v_pk_fma_f32 v[150:151], v[84:85], v[176:177], v[150:151] op_sel:[0,0,1] op_sel_hi:[1,1,0]
	v_pk_fma_f32 v[148:149], v[82:83], v[174:175], v[148:149] op_sel:[0,0,1] op_sel_hi:[1,1,0]
	s_nop 0
	v_pk_add_f32 v[148:149], v[148:149], v[150:151]
	s_waitcnt lgkmcnt(1)
	v_pk_mul_f32 v[150:151], v[128:129], v[188:189]
	v_pk_add_f32 v[68:69], v[68:69], v[148:149]
	v_pk_mul_f32 v[148:149], v[126:127], v[186:187]
	v_pk_fma_f32 v[150:151], v[88:89], v[188:189], v[150:151] op_sel:[0,0,1] op_sel_hi:[1,1,0]
	v_pk_fma_f32 v[148:149], v[86:87], v[186:187], v[148:149] op_sel:[0,0,1] op_sel_hi:[1,1,0]
	s_nop 0
	v_pk_add_f32 v[148:149], v[148:149], v[150:151]
	s_waitcnt lgkmcnt(0)
	v_pk_mul_f32 v[150:151], v[140:141], v[220:221]
	v_pk_add_f32 v[68:69], v[68:69], v[148:149]
	v_pk_mul_f32 v[148:149], v[138:139], v[218:219]
	v_pk_fma_f32 v[150:151], v[92:93], v[220:221], v[150:151] op_sel:[0,0,1] op_sel_hi:[1,1,0]
	v_pk_fma_f32 v[148:149], v[90:91], v[218:219], v[148:149] op_sel:[0,0,1] op_sel_hi:[1,1,0]
	s_nop 0
	v_pk_add_f32 v[148:149], v[148:149], v[150:151]
	s_nop 0
	v_pk_add_f32 v[166:167], v[68:69], v[148:149]
	ds_read_b128 v[148:151], v66 offset:22528
	s_waitcnt lgkmcnt(0)
	v_pk_mul_f32 v[68:69], v[106:107], v[148:149]
	s_nop 0
	v_pk_fma_f32 v[68:69], v[94:95], v[148:149], v[68:69] op_sel:[0,0,1] op_sel_hi:[1,1,0]
	v_pk_mul_f32 v[148:149], v[108:109], v[150:151]
	s_nop 0
	v_pk_fma_f32 v[148:149], v[96:97], v[150:151], v[148:149] op_sel:[0,0,1] op_sel_hi:[1,1,0]
	s_nop 0
	v_pk_add_f32 v[168:169], v[68:69], v[148:149]
	ds_read_b128 v[148:151], v66 offset:23552
	s_waitcnt lgkmcnt(0)
	v_pk_mul_f32 v[68:69], v[104:105], v[148:149]
	s_nop 0
	v_pk_fma_f32 v[170:171], v[98:99], v[148:149], v[68:69] op_sel:[0,0,1] op_sel_hi:[1,1,0]
	v_pk_mul_f32 v[68:69], v[102:103], v[150:151]
	s_nop 0
	v_pk_fma_f32 v[172:173], v[100:101], v[150:151], v[68:69] op_sel:[0,0,1] op_sel_hi:[1,1,0]
	ds_read_b128 v[148:151], v66 offset:24576
	ds_read_b128 v[174:177], v66 offset:25600
	ds_read_b128 v[186:189], v66 offset:26624
	ds_read_b128 v[218:221], v66 offset:27648
	ds_read_b128 v[222:225], v66 offset:28672
	ds_read_b128 v[226:229], v66 offset:29696
	s_waitcnt lgkmcnt(5)
	v_pk_mul_f32 v[68:69], v[110:111], v[148:149]
	s_nop 0
	v_pk_fma_f32 v[68:69], v[70:71], v[148:149], v[68:69] op_sel:[0,0,1] op_sel_hi:[1,1,0]
	v_pk_mul_f32 v[148:149], v[112:113], v[150:151]
	s_nop 0
	v_pk_fma_f32 v[148:149], v[72:73], v[150:151], v[148:149] op_sel:[0,0,1] op_sel_hi:[1,1,0]
	s_waitcnt lgkmcnt(4)
; #define LAS __attribute__((address_space(3)))
; __device__ __forceinline__ void ln1_router(Frame& F, int l, int nrows) {
;     ...
;             for (int k = 0; k < 4; ++k) { float x0 = 0.f, x1 = 0.f; const LAS float* wp = RW + (4 * g + k) * DM + 4 * F.lane;
; #pragma unroll
;                 for (int j = 0; j < 8; ++j) { const f32x4 w4 = *(const LAS f32x4*)(wp + 256 * j);
;                     x0 += (v[0][j][0] * w4[0] + v[0][j][1] * w4[1]) + (v[0][j][2] * w4[2] + v[0][j][3] * w4[3]);
;                     x1 += (v[1][j][0] * w4[0] + v[1][j][1] * w4[1]) + (v[1][j][2] * w4[2] + v[1][j][3] * w4[3]); }
;                 a0[k] = x0; a1[k] = x1; }
;             const bool u0 = F.lane & 1, u1 = (F.lane >> 1) & 1;
;             float b00 = (u0 ? a0[1] : a0[0]) + __shfl_xor(u0 ? a0[0] : a0[1], 1), b01 = (u0 ? a0[3] : a0[2]) + __shfl_xor(u0 ? a0[2] : a0[3], 1);
;             float b10 = (u0 ? a1[1] : a1[0]) + __shfl_xor(u0 ? a1[0] : a1[1], 1), b11 = (u0 ? a1[3] : a1[2]) + __shfl_xor(u0 ? a1[2] : a1[3], 1);
;             float c0 = (u1 ? b01 : b00) + __shfl_xor(u1 ? b00 : b01, 2), c1 = (u1 ? b11 : b10) + __shfl_xor(u1 ? b10 : b11, 2);
; #pragma unroll
;             for (int o = 4; o < 64; o <<= 1) { c0 += __shfl_xor(c0, o); c1 += __shfl_xor(c1, o); }
;             const bool sel = ((F.lane >> 2) & 3) == g; mine0 = sel ? c0 : mine0; mine1 = sel ? c1 : mine1;
	v_pk_mul_f32 v[150:151], v[116:117], v[176:177]
	v_pk_add_f32 v[68:69], v[68:69], v[148:149]
	v_pk_mul_f32 v[148:149], v[114:115], v[174:175]
	v_pk_fma_f32 v[150:151], v[76:77], v[176:177], v[150:151] op_sel:[0,0,1] op_sel_hi:[1,1,0]
	v_pk_fma_f32 v[148:149], v[74:75], v[174:175], v[148:149] op_sel:[0,0,1] op_sel_hi:[1,1,0]
	v_pk_add_f32 v[68:69], v[68:69], 0 op_sel_hi:[1,0]
	v_pk_add_f32 v[148:149], v[148:149], v[150:151]
	s_waitcnt lgkmcnt(3)
	v_pk_mul_f32 v[150:151], v[120:121], v[188:189]
	v_pk_add_f32 v[68:69], v[68:69], v[148:149]
	v_pk_mul_f32 v[148:149], v[118:119], v[186:187]
	v_pk_fma_f32 v[150:151], v[80:81], v[188:189], v[150:151] op_sel:[0,0,1] op_sel_hi:[1,1,0]
	v_pk_fma_f32 v[148:149], v[78:79], v[186:187], v[148:149] op_sel:[0,0,1] op_sel_hi:[1,1,0]
	s_nop 0
	v_pk_add_f32 v[148:149], v[148:149], v[150:151]
	s_waitcnt lgkmcnt(2)
	v_pk_mul_f32 v[150:151], v[124:125], v[220:221]
	v_pk_add_f32 v[68:69], v[68:69], v[148:149]
	v_pk_mul_f32 v[148:149], v[122:123], v[218:219]
	v_pk_fma_f32 v[150:151], v[84:85], v[220:221], v[150:151] op_sel:[0,0,1] op_sel_hi:[1,1,0]
	v_pk_fma_f32 v[148:149], v[82:83], v[218:219], v[148:149] op_sel:[0,0,1] op_sel_hi:[1,1,0]
	s_nop 0
	v_pk_add_f32 v[148:149], v[148:149], v[150:151]
	s_waitcnt lgkmcnt(1)
	v_pk_mul_f32 v[150:151], v[128:129], v[224:225]
	v_pk_add_f32 v[68:69], v[68:69], v[148:149]
	v_pk_mul_f32 v[148:149], v[126:127], v[222:223]
	v_pk_fma_f32 v[150:151], v[88:89], v[224:225], v[150:151] op_sel:[0,0,1] op_sel_hi:[1,1,0]
	v_pk_fma_f32 v[148:149], v[86:87], v[222:223], v[148:149] op_sel:[0,0,1] op_sel_hi:[1,1,0]
	s_nop 0
	v_pk_add_f32 v[148:149], v[148:149], v[150:151]
	s_waitcnt lgkmcnt(0)
	v_pk_mul_f32 v[150:151], v[140:141], v[228:229]
	v_pk_add_f32 v[68:69], v[68:69], v[148:149]
	v_pk_mul_f32 v[148:149], v[138:139], v[226:227]
	v_pk_fma_f32 v[150:151], v[92:93], v[228:229], v[150:151] op_sel:[0,0,1] op_sel_hi:[1,1,0]
	v_pk_fma_f32 v[148:149], v[90:91], v[226:227], v[148:149] op_sel:[0,0,1] op_sel_hi:[1,1,0]
	s_nop 0
	v_pk_add_f32 v[148:149], v[148:149], v[150:151]
	s_nop 0
	v_pk_add_f32 v[174:175], v[68:69], v[148:149]
	ds_read_b128 v[148:151], v66 offset:30720
	s_waitcnt lgkmcnt(0)
	v_pk_mul_f32 v[68:69], v[106:107], v[148:149]
	s_nop 0
	v_pk_fma_f32 v[68:69], v[94:95], v[148:149], v[68:69] op_sel:[0,0,1] op_sel_hi:[1,1,0]
	v_pk_mul_f32 v[148:149], v[108:109], v[150:151]
	s_nop 0
	v_pk_fma_f32 v[148:149], v[96:97], v[150:151], v[148:149] op_sel:[0,0,1] op_sel_hi:[1,1,0]
	v_pk_add_f32 v[150:151], v[170:171], v[172:173]
	v_pk_add_f32 v[176:177], v[68:69], v[148:149]
	ds_read_b128 v[66:69], v66 offset:31744
	s_waitcnt lgkmcnt(0)
	v_pk_mul_f32 v[148:149], v[104:105], v[66:67]
	s_nop 0
	v_pk_fma_f32 v[66:67], v[98:99], v[66:67], v[148:149] op_sel:[0,0,1] op_sel_hi:[1,1,0]
	v_pk_mul_f32 v[148:149], v[102:103], v[68:69]
	s_nop 0
	v_pk_fma_f32 v[68:69], v[100:101], v[68:69], v[148:149] op_sel:[0,0,1] op_sel_hi:[1,1,0]
	v_pk_add_f32 v[148:149], v[162:163], v[164:165]
	v_pk_add_f32 v[66:67], v[66:67], v[68:69]
	v_pk_add_f32 v[144:145], v[144:145], v[148:149]
	v_pk_add_f32 v[148:149], v[166:167], v[168:169]
	v_cndmask_b32_e64 v68, v143, v145, s[44:45]
	v_pk_add_f32 v[148:149], v[148:149], v[150:151]
	v_pk_add_f32 v[150:151], v[174:175], v[176:177]
	s_nop 1
	v_mov_b32_dpp v69, v68 quad_perm:[1,0,3,2] row_mask:0xf bank_mask:0xf
	v_pk_add_f32 v[66:67], v[150:151], v[66:67]
	v_cndmask_b32_e64 v154, v144, v142, s[44:45]
	v_cndmask_b32_e64 v68, v149, v67, s[44:45]
	s_nop 1
	v_mov_b32_dpp v151, v68 quad_perm:[1,0,3,2] row_mask:0xf bank_mask:0xf
	v_cndmask_b32_e64 v68, v142, v144, s[44:45]
	v_cndmask_b32_e64 v142, v66, v148, s[44:45]
	v_cndmask_b32_e64 v66, v148, v66, s[44:45]
	s_nop 1
	v_mov_b32_dpp v68, v68 quad_perm:[1,0,3,2] row_mask:0xf bank_mask:0xf
	s_nop 1
	v_mov_b32_dpp v150, v66 quad_perm:[1,0,3,2] row_mask:0xf bank_mask:0xf
	v_cndmask_b32_e64 v155, v145, v143, s[44:45]
	v_cndmask_b32_e64 v143, v67, v149, s[44:45]
	s_waitcnt lgkmcnt(0)
	v_pk_add_f32 v[68:69], v[154:155], v[68:69]
	s_waitcnt lgkmcnt(0)
	v_pk_add_f32 v[66:67], v[142:143], v[150:151]
	s_nop 0
	v_cndmask_b32_e64 v142, v69, v67, s[46:47]
	v_cndmask_b32_e64 v144, v66, v68, s[46:47]
	v_cndmask_b32_e64 v66, v68, v66, s[46:47]
	s_nop 1
	v_mov_b32_dpp v143, v142 quad_perm:[2,3,0,1] row_mask:0xf bank_mask:0xf
	s_nop 1
	v_mov_b32_dpp v142, v66 quad_perm:[2,3,0,1] row_mask:0xf bank_mask:0xf
	v_cndmask_b32_e64 v145, v67, v69, s[46:47]
	s_waitcnt lgkmcnt(0)
	v_pk_add_f32 v[66:67], v[144:145], v[142:143]
	s_nop 1
	v_mov_b32_dpp v69, v67 row_half_mirror row_mask:0xf bank_mask:0xf
	s_nop 1
	v_mov_b32_dpp v69, v69 quad_perm:[3,2,1,0] row_mask:0xf bank_mask:0xf
	s_nop 1
	v_mov_b32_dpp v68, v66 row_half_mirror row_mask:0xf bank_mask:0xf
	s_nop 1
	v_mov_b32_dpp v68, v68 quad_perm:[3,2,1,0] row_mask:0xf bank_mask:0xf
	s_waitcnt lgkmcnt(0)
	v_pk_add_f32 v[66:67], v[66:67], v[68:69]
	s_nop 1
	v_mov_b32_dpp v69, v67 row_ror:8 row_mask:0xf bank_mask:0xf
	s_nop 1
	v_mov_b32_dpp v68, v66 row_ror:8 row_mask:0xf bank_mask:0xf
	s_waitcnt lgkmcnt(0)
	v_pk_add_f32 v[66:67], v[66:67], v[68:69]
	v_mov_b32_e32 v69, v67
	s_nop 1
	v_permlane16_swap_b32_e32 v67, v69
	v_mov_b32_e32 v68, v66
	s_nop 1
	v_permlane16_swap_b32_e32 v66, v68
	s_waitcnt lgkmcnt(0)
	v_pk_add_f32 v[66:67], v[66:67], v[68:69]
	v_mov_b32_e32 v69, v67
	s_nop 1
	v_permlane32_swap_b32_e32 v67, v69
	v_mov_b32_e32 v68, v66
	s_nop 1
	v_permlane32_swap_b32_e32 v66, v68
	s_waitcnt lgkmcnt(0)
	v_pk_add_f32 v[66:67], v[66:67], v[68:69]
	s_nop 0
	v_cndmask_b32_e32 v216, v216, v66, vcc
	v_cndmask_b32_e32 v217, v217, v67, vcc
	s_cbranch_scc0 .LBB0_1319
; __device__ __forceinline__ float router_softmax(float mine) {
;     float mx = mine;
;     mx = fmaxf(mx, __shfl_xor(mx, 1)); mx = fmaxf(mx, __shfl_xor(mx, 2)); mx = fmaxf(mx, __shfl_xor(mx, 4)); mx = fmaxf(mx, __shfl_xor(mx, 8));
;     const float ex = expf(mine - mx);
;     float den = ex;
;     den += __shfl_xor(den, 1); den += __shfl_xor(den, 2); den += __shfl_xor(den, 4); den += __shfl_xor(den, 8);
;     return ex / den;
; }
; __device__ __forceinline__ void router_store(Frame& F, float affv, int row, bool doit) {
;     float* AFF = (float*)(F.ws + WS_AFF); float* AFFC = (float*)(F.ws + WS_AFFC);
;     if (F.lane < 16 && doit) { if (row < NLAT) AFF[((size_t)(row >> 13) * NEXP + F.lane) * SEQ + (row & (SEQ - 1))] = affv;
;                        else { const int rc = row - NLAT; AFFC[((size_t)(rc >> 8) * NEXP + F.lane) * CTXL + (rc & (CTXL - 1))] = affv; } }
; __device__ __forceinline__ void ln1_router(Frame& F, int l, int nrows) {
;     ...
;         paff0 = router_softmax(mine0); paff1 = router_softmax(mine1);
;         if (row0 + 2 * NGW >= nrows) { router_store(F, paff0, rows[0], true); router_store(F, paff1, rows[1], has1); }
	s_nop 1
	v_mov_b32_dpp v66, v217 quad_perm:[1,0,3,2] row_mask:0xf bank_mask:0xf
	v_max_f32_e32 v67, v217, v217
	s_mov_b32 s0, 0x3fb8aa3b
	s_mov_b32 s1, 0xc2ce8ed0
	s_mov_b32 s9, 0x42b17218
	s_waitcnt lgkmcnt(0)
	v_max_f32_e32 v66, v66, v66
	v_max_f32_e32 v66, v67, v66
	s_nop 1
	v_mov_b32_dpp v67, v66 quad_perm:[2,3,0,1] row_mask:0xf bank_mask:0xf
	s_waitcnt lgkmcnt(0)
	v_max_f32_e32 v67, v67, v67
	v_max_f32_e32 v66, v66, v67
	s_nop 1
	v_mov_b32_dpp v67, v66 row_half_mirror row_mask:0xf bank_mask:0xf
	s_nop 1
	v_mov_b32_dpp v67, v67 quad_perm:[3,2,1,0] row_mask:0xf bank_mask:0xf
	s_waitcnt lgkmcnt(0)
	v_max_f32_e32 v67, v67, v67
	v_max_f32_e32 v66, v66, v67
	s_nop 1
	v_mov_b32_dpp v67, v66 row_ror:8 row_mask:0xf bank_mask:0xf
	s_waitcnt lgkmcnt(0)
	v_max_f32_e32 v67, v67, v67
	v_max_f32_e32 v66, v66, v67
	v_sub_f32_e32 v66, v217, v66
	v_mul_f32_e32 v67, 0x3fb8aa3b, v66
	v_fma_f32 v68, v66, s0, -v67
	v_rndne_f32_e32 v69, v67
	v_fmac_f32_e32 v68, 0x32a5705f, v66
	v_sub_f32_e32 v67, v67, v69
	v_add_f32_e32 v67, v67, v68
	v_exp_f32_e32 v67, v67
	v_cvt_i32_f32_e32 v68, v69
	v_cmp_ngt_f32_e32 vcc, s1, v66
	v_ldexp_f32 v67, v67, v68
	s_nop 0
	v_cndmask_b32_e32 v67, 0, v67, vcc
	v_cmp_nlt_f32_e32 vcc, s9, v66
	s_nop 1
	v_mov_b32_dpp v66, v216 quad_perm:[1,0,3,2] row_mask:0xf bank_mask:0xf
	v_max_f32_e32 v68, v216, v216
	v_cndmask_b32_e32 v67, v183, v67, vcc
	s_nop 1
	v_mov_b32_dpp v69, v67 quad_perm:[1,0,3,2] row_mask:0xf bank_mask:0xf
	s_waitcnt lgkmcnt(0)
	v_max_f32_e32 v66, v66, v66
	v_max_f32_e32 v66, v68, v66
	s_nop 1
	v_mov_b32_dpp v68, v66 quad_perm:[2,3,0,1] row_mask:0xf bank_mask:0xf
	s_waitcnt lgkmcnt(0)
	v_max_f32_e32 v68, v68, v68
	v_max_f32_e32 v66, v66, v68
	s_nop 1
	v_mov_b32_dpp v68, v66 row_half_mirror row_mask:0xf bank_mask:0xf
	s_nop 1
	v_mov_b32_dpp v68, v68 quad_perm:[3,2,1,0] row_mask:0xf bank_mask:0xf
	s_waitcnt lgkmcnt(0)
	v_max_f32_e32 v68, v68, v68
	v_max_f32_e32 v66, v66, v68
	s_nop 1
	v_mov_b32_dpp v68, v66 row_ror:8 row_mask:0xf bank_mask:0xf
	s_waitcnt lgkmcnt(0)
	v_max_f32_e32 v68, v68, v68
	v_max_f32_e32 v66, v66, v68
	v_sub_f32_e32 v66, v216, v66
	v_mul_f32_e32 v68, 0x3fb8aa3b, v66
	v_fma_f32 v70, v66, s0, -v68
	v_rndne_f32_e32 v71, v68
	v_fmac_f32_e32 v70, 0x32a5705f, v66
	v_sub_f32_e32 v68, v68, v71
	v_add_f32_e32 v68, v68, v70
	v_exp_f32_e32 v68, v68
	v_cvt_i32_f32_e32 v70, v71
	v_cmp_ngt_f32_e32 vcc, s1, v66
	v_ldexp_f32 v68, v68, v70
	s_nop 0
	v_cndmask_b32_e32 v68, 0, v68, vcc
	v_cmp_nlt_f32_e32 vcc, s9, v66
	s_nop 1
	v_cndmask_b32_e32 v66, v183, v68, vcc
	s_nop 1
	v_mov_b32_dpp v68, v66 quad_perm:[1,0,3,2] row_mask:0xf bank_mask:0xf
	s_waitcnt lgkmcnt(0)
	v_pk_add_f32 v[68:69], v[66:67], v[68:69]
	s_nop 1
	v_mov_b32_dpp v71, v69 quad_perm:[2,3,0,1] row_mask:0xf bank_mask:0xf
	s_nop 1
	v_mov_b32_dpp v70, v68 quad_perm:[2,3,0,1] row_mask:0xf bank_mask:0xf
	s_waitcnt lgkmcnt(0)
	v_pk_add_f32 v[68:69], v[68:69], v[70:71]
	s_nop 1
	v_mov_b32_dpp v71, v69 row_half_mirror row_mask:0xf bank_mask:0xf
	s_nop 1
	v_mov_b32_dpp v71, v71 quad_perm:[3,2,1,0] row_mask:0xf bank_mask:0xf
	s_nop 1
	v_mov_b32_dpp v70, v68 row_half_mirror row_mask:0xf bank_mask:0xf
	s_nop 1
	v_mov_b32_dpp v70, v70 quad_perm:[3,2,1,0] row_mask:0xf bank_mask:0xf
	s_waitcnt lgkmcnt(0)
	v_pk_add_f32 v[68:69], v[68:69], v[70:71]
	s_nop 1
	v_mov_b32_dpp v71, v69 row_ror:8 row_mask:0xf bank_mask:0xf
	s_nop 1
	v_mov_b32_dpp v70, v68 row_ror:8 row_mask:0xf bank_mask:0xf
	s_waitcnt lgkmcnt(0)
	v_pk_add_f32 v[68:69], v[68:69], v[70:71]
	s_nop 0
	v_div_scale_f32 v70, s[0:1], v69, v69, v67
	v_rcp_f32_e32 v71, v70
	s_nop 0
	v_fma_f32 v72, -v70, v71, 1.0
	v_fmac_f32_e32 v71, v72, v71
	v_div_scale_f32 v72, vcc, v67, v69, v67
	v_mul_f32_e32 v73, v72, v71
	v_fma_f32 v74, -v70, v73, v72
	v_fmac_f32_e32 v73, v74, v71
	v_fma_f32 v70, -v70, v73, v72
	v_div_fmas_f32 v70, v70, v71, v73
	v_div_fixup_f32 v139, v70, v69, v67
	v_div_scale_f32 v67, s[0:1], v68, v68, v66
	v_rcp_f32_e32 v69, v67
	s_nop 0
	v_fma_f32 v70, -v67, v69, 1.0
	v_fmac_f32_e32 v69, v70, v69
	v_div_scale_f32 v70, vcc, v66, v68, v66
	v_mul_f32_e32 v71, v70, v69
	v_fma_f32 v72, -v67, v71, v70
	v_fmac_f32_e32 v71, v72, v69
	v_fma_f32 v67, -v67, v71, v70
	v_div_fmas_f32 v67, v67, v69, v71
	v_div_fixup_f32 v138, v67, v68, v66
	s_and_b64 vcc, exec, s[12:13]
	s_cbranch_vccz .LBB0_1296
	s_and_saveexec_b64 s[0:1], s[42:43]
	s_cbranch_execz .LBB0_1326
	s_cmpk_gt_i32 s8, 0x3fff
	s_mov_b64 s[12:13], -1
	s_cbranch_scc0 .LBB0_1324
	s_add_i32 s9, s8, 0xffffc000
	s_lshr_b32 s9, s9, 4
	s_and_b32 s9, s9, 0xffffff0
	v_or_b32_e32 v146, s9, v1
	v_readlane_b32 s12, v251, 39
	s_and_b32 s9, s8, 0xff
	v_lshlrev_b64 v[66:67], 10, v[146:147]
	v_readlane_b32 s13, v251, 40
	s_lshl_b32 s58, s9, 2
	s_nop 0
	v_lshl_add_u64 v[66:67], s[12:13], 0, v[66:67]
	v_lshl_add_u64 v[66:67], v[66:67], 0, s[58:59]
	global_store_dword v[66:67], v139, off
	s_mov_b64 s[12:13], 0
